# v9 plus RWKV producer P4 reordered: operand reads hoisted and the four independent MFMAs issued inside the dependent chain latency
# speedup vs baseline: 1.0139x; 1.0027x over previous
; #define LAS __attribute__((address_space(3)))
; __device__ __forceinline__ f32x4 bf4(v2u u) { return (f32x4){bflo(u.x), bfhi(u.x), bflo(u.y), bfhi(u.y)}; }
; __device__ __forceinline__ float row16_sum(float x) { x += dpp_f<0xB1>(x); x += dpp_f<0x4E>(x); x += dpp_f<0x141>(x); x += dpp_f<0x140>(x); return x; }
; __device__ __forceinline__ void rw_scan(const bf16* R, const bf16* K, const bf16* V, const bf16* WM, const bf16* A, const float* k_k, const float* k_a, bf16* Y, LAS unsigned char* lds) {
;     ...
;                     LAS unsigned char* slot = lds + (cj % RW_NSLOT) * RWS_SLOT;
;                     f32x4 wv[4], kk[4], km[4], be[4], rr[4];
; #pragma unroll
;                     for (int j = 0; j < 4; ++j) {
;                         const f32x4 r = bf4(cu.r[j]), k = bf4(cu.k[j]), wm = bf4(cu.wm[j]), a = bf4(cu.a[j]);
;                         const f32x4 kr = k * kkc;
;                         const float n2 = row16_sum((kr[0] * kr[0] + kr[1] * kr[1]) + (kr[2] * kr[2] + kr[3] * kr[3]));
;                         const float inv = 1.0f / fmaxf(sqrtf(n2), 1e-12f);
;                         kk[j] = kr * inv; be[j] = kk[j] * a; km[j] = k * (1.0f + (a - 1.0f) * kac); wv[j] = 1.0f - wm; rr[j] = r;
;                     }
.LBB0_498:
	s_waitcnt vmcnt(21)
	v_lshlrev_b32_e32 v92, 16, v70
	v_and_b32_e32 v93, 0xffff0000, v70
	v_lshlrev_b32_e32 v94, 16, v71
	v_and_b32_e32 v95, 0xffff0000, v71
	v_pk_mul_f32 v[70:71], v[0:1], v[92:93]
	v_pk_mul_f32 v[72:73], v[2:3], v[94:95]
	v_lshlrev_b32_e32 v34, 16, v66
	v_and_b32_e32 v88, 0xffff0000, v66
	v_lshlrev_b32_e32 v89, 16, v67
	v_and_b32_e32 v90, 0xffff0000, v67
	v_pk_mul_f32 v[66:67], v[72:73], v[72:73]
	v_pk_mul_f32 v[82:83], v[70:71], v[70:71]
	v_sub_f32_e32 v103, 1.0, v90
	v_pk_mov_b32 v[86:87], v[82:83], v[66:67] op_sel:[1,0]
	v_mov_b32_e32 v83, v67
	v_pk_add_f32 v[66:67], v[86:87], v[82:83]
	v_lshlrev_b32_e32 v82, 16, v80
	v_and_b32_e32 v83, 0xffff0000, v80
	v_lshlrev_b32_e32 v90, 16, v81
	v_and_b32_e32 v91, 0xffff0000, v81
	v_lshlrev_b32_e32 v112, 16, v78
	v_and_b32_e32 v113, 0xffff0000, v78
	v_lshlrev_b32_e32 v114, 16, v79
	v_and_b32_e32 v115, 0xffff0000, v79
	v_pk_mul_f32 v[78:79], v[0:1], v[82:83]
	v_pk_mul_f32 v[80:81], v[2:3], v[90:91]
	v_sub_f32_e32 v101, 1.0, v88
	v_sub_f32_e32 v102, 1.0, v89
	v_pk_mul_f32 v[86:87], v[80:81], v[80:81]
	v_pk_mul_f32 v[88:89], v[78:79], v[78:79]
	v_sub_f32_e32 v100, 1.0, v34
	v_pk_mov_b32 v[110:111], v[88:89], v[86:87] op_sel:[1,0]
	v_mov_b32_e32 v89, v87
	v_pk_add_f32 v[86:87], v[110:111], v[88:89]
	s_mul_hi_u32 s68, s89, 0x38e38e39
	v_add_f32_e32 v34, v86, v87
	s_lshr_b32 s68, s68, 1
	s_mul_i32 s68, s68, 9
	v_add_f32_dpp v34, v34, v34 quad_perm:[1,0,3,2] row_mask:0xf bank_mask:0xf bound_ctrl:1
	s_sub_i32 s92, s89, s68
	v_lshlrev_b32_e32 v108, 16, v74
	v_add_f32_dpp v34, v34, v34 quad_perm:[2,3,0,1] row_mask:0xf bank_mask:0xf bound_ctrl:1
	v_and_b32_e32 v109, 0xffff0000, v74
	v_and_b32_e32 v111, 0xffff0000, v107
	v_add_f32_dpp v34, v34, v34 row_half_mirror row_mask:0xf bank_mask:0xf bound_ctrl:1
	v_lshlrev_b32_e32 v120, 16, v104
	v_and_b32_e32 v121, 0xffff0000, v104
	v_add_f32_dpp v34, v34, v34 row_mirror row_mask:0xf bank_mask:0xf bound_ctrl:1
	v_cmp_gt_f32_e32 vcc, s24, v34
	v_mul_f32_e32 v86, 0x4f800000, v34
	v_lshlrev_b32_e32 v122, 16, v105
	v_cndmask_b32_e32 v34, v34, v86, vcc
	v_sqrt_f32_e32 v86, v34
	v_and_b32_e32 v123, 0xffff0000, v105
	v_sub_f32_e32 v127, 1.0, v113
	v_sub_f32_e32 v126, 1.0, v112
	v_add_u32_e32 v87, -1, v86
	v_fma_f32 v88, -v87, v86, v34
	v_cmp_ge_f32_e64 s[68:69], 0, v88
	v_add_u32_e32 v88, 1, v86
	v_sub_f32_e32 v129, 1.0, v115
	v_cndmask_b32_e64 v87, v86, v87, s[68:69]
	v_fma_f32 v86, -v88, v86, v34
	v_cmp_lt_f32_e64 s[68:69], 0, v86
	v_sub_f32_e32 v128, 1.0, v114
	v_lshlrev_b32_e32 v116, 16, v98
	v_cndmask_b32_e64 v86, v87, v88, s[68:69]
	v_mul_f32_e32 v87, 0x37800000, v86
	v_cndmask_b32_e32 v86, v86, v87, vcc
	v_cmp_class_f32_e32 vcc, v34, v229
	v_and_b32_e32 v117, 0xffff0000, v98
	v_sub_f32_e32 v133, 1.0, v121
	v_cndmask_b32_e32 v34, v86, v34, vcc
	v_max_f32_e32 v34, 0x2b8cbccc, v34
	v_div_scale_f32 v86, s[68:69], v34, v34, 1.0
	v_rcp_f32_e32 v87, v86
	v_sub_f32_e32 v132, 1.0, v120
	v_lshlrev_b32_e32 v120, 16, v85
	v_and_b32_e32 v121, 0xffff0000, v85
	v_fma_f32 v88, -v86, v87, 1.0
	v_fmac_f32_e32 v87, v88, v87
	v_div_scale_f32 v88, vcc, 1.0, v34, 1.0
	v_mul_f32_e32 v89, v88, v87
	v_fma_f32 v110, -v86, v89, v88
	v_fmac_f32_e32 v89, v110, v87
	v_fma_f32 v86, -v86, v89, v88
	v_div_fmas_f32 v86, v86, v87, v89
	v_div_fixup_f32 v34, v86, v34, 1.0
	v_pk_mul_f32 v[88:89], v[78:79], v[34:35] op_sel_hi:[1,0]
	v_lshlrev_b32_e32 v110, 16, v107
	v_pk_mul_f32 v[78:79], v[88:89], v[108:109]
	v_pk_add_f32 v[108:109], v[108:109], -1.0 op_sel_hi:[1,0]
	v_pk_mul_f32 v[86:87], v[80:81], v[34:35] op_sel_hi:[1,0]
	v_pk_fma_f32 v[108:109], v[4:5], v[108:109], 1.0 op_sel_hi:[1,1,0]
	v_sub_f32_e32 v131, 1.0, v123
	v_pk_mul_f32 v[82:83], v[108:109], v[82:83]
	v_lshlrev_b32_e32 v108, 16, v106
	v_and_b32_e32 v109, 0xffff0000, v106
	v_pk_mul_f32 v[104:105], v[0:1], v[108:109]
	v_pk_mul_f32 v[106:107], v[2:3], v[110:111]
	v_pk_mul_f32 v[114:115], v[104:105], v[104:105]
	v_pk_mul_f32 v[112:113], v[106:107], v[106:107]
	v_sub_f32_e32 v130, 1.0, v122
	v_pk_mov_b32 v[118:119], v[114:115], v[112:113] op_sel:[1,0]
	v_mov_b32_e32 v115, v113
	v_pk_add_f32 v[112:113], v[118:119], v[114:115]
	v_and_b32_e32 v119, 0xffff0000, v84
	v_add_f32_e32 v34, v112, v113
	v_lshlrev_b32_e32 v136, 16, v10
	v_and_b32_e32 v137, 0xffff0000, v10
	v_add_f32_dpp v34, v34, v34 quad_perm:[1,0,3,2] row_mask:0xf bank_mask:0xf bound_ctrl:1
	v_lshlrev_b32_e32 v164, 16, v11
	v_and_b32_e32 v165, 0xffff0000, v11
	v_add_f32_dpp v34, v34, v34 quad_perm:[2,3,0,1] row_mask:0xf bank_mask:0xf bound_ctrl:1
	v_lshlrev_b32_e32 v10, 16, v8
	v_and_b32_e32 v11, 0xffff0000, v8
	v_add_f32_dpp v34, v34, v34 row_half_mirror row_mask:0xf bank_mask:0xf bound_ctrl:1
	v_lshlrev_b32_e32 v8, 16, v9
	v_and_b32_e32 v9, 0xffff0000, v9
	v_add_f32_dpp v34, v34, v34 row_mirror row_mask:0xf bank_mask:0xf bound_ctrl:1
	v_cmp_gt_f32_e32 vcc, s24, v34
	v_mul_f32_e32 v112, 0x4f800000, v34
	v_pk_mul_f32 v[166:167], v[100:101], v[126:127]
	v_cndmask_b32_e32 v34, v34, v112, vcc
	v_sqrt_f32_e32 v112, v34
	v_pk_mul_f32 v[132:133], v[166:167], v[132:133]
	v_add_f32_e32 v66, v66, v67
	s_mul_i32 s74, s92, 0x2c00
	v_add_u32_e32 v113, -1, v112
	v_fma_f32 v114, -v113, v112, v34
	v_cmp_ge_f32_e64 s[68:69], 0, v114
	v_add_u32_e32 v114, 1, v112
	v_add_f32_dpp v66, v66, v66 quad_perm:[1,0,3,2] row_mask:0xf bank_mask:0xf bound_ctrl:1
	v_cndmask_b32_e64 v113, v112, v113, s[68:69]
	v_fma_f32 v112, -v114, v112, v34
	v_cmp_lt_f32_e64 s[68:69], 0, v112
	v_add_f32_dpp v66, v66, v66 quad_perm:[2,3,0,1] row_mask:0xf bank_mask:0xf bound_ctrl:1
	s_waitcnt vmcnt(20)
; __device__ __forceinline__ f32x4 bf4(v2u u) { return (f32x4){bflo(u.x), bfhi(u.x), bflo(u.y), bfhi(u.y)}; }
; __device__ __forceinline__ float row16_sum(float x) { x += dpp_f<0xB1>(x); x += dpp_f<0x4E>(x); x += dpp_f<0x141>(x); x += dpp_f<0x140>(x); return x; }
; __device__ __forceinline__ void rw_scan(const bf16* R, const bf16* K, const bf16* V, const bf16* WM, const bf16* A, const float* k_k, const float* k_a, bf16* Y, LAS unsigned char* lds) {
;     ...
;                     for (int j = 0; j < 4; ++j) {
;                         const f32x4 r = bf4(cu.r[j]), k = bf4(cu.k[j]), wm = bf4(cu.wm[j]), a = bf4(cu.a[j]);
;                         const f32x4 kr = k * kkc;
;                         const float n2 = row16_sum((kr[0] * kr[0] + kr[1] * kr[1]) + (kr[2] * kr[2] + kr[3] * kr[3]));
;                         const float inv = 1.0f / fmaxf(sqrtf(n2), 1e-12f);
;                         kk[j] = kr * inv; be[j] = kk[j] * a; km[j] = k * (1.0f + (a - 1.0f) * kac); wv[j] = 1.0f - wm; rr[j] = r;
;                     }
;                     f32x4 g[4]; g[0] = wv[0]; g[1] = g[0] * wv[1]; g[2] = g[1] * wv[2]; g[3] = g[2] * wv[3];
;                     f32x4 pre = (f32x4){1.f, 1.f, 1.f, 1.f}, all = (f32x4){1.f, 1.f, 1.f, 1.f};
; #pragma unroll
;                     for (int x = 0; x < 4; ++x) {
;                         const float t0 = __shfl(g[3][x], fr), t1 = __shfl(g[3][x], 16 + fr), t2 = __shfl(g[3][x], 32 + fr), t3 = __shfl(g[3][x], 48 + fr);
;                         float p = 1.f; if (fq > 0) p *= t0; if (fq > 1) p *= t1; if (fq > 2) p *= t2;
;                         pre[x] = p; all[x] = (t0 * t1) * (t2 * t3);
;                     }
	v_and_b32_e32 v175, 0xffff0000, v33
	v_cndmask_b32_e64 v112, v113, v114, s[68:69]
	v_mul_f32_e32 v113, 0x37800000, v112
	v_cndmask_b32_e32 v112, v112, v113, vcc
	v_cmp_class_f32_e32 vcc, v34, v229
	v_add_f32_dpp v202, v66, v66 row_half_mirror row_mask:0xf bank_mask:0xf bound_ctrl:1
	s_add_i32 s74, s74, 0
	v_cndmask_b32_e32 v34, v112, v34, vcc
	v_max_f32_e32 v34, 0x2b8cbccc, v34
	v_div_scale_f32 v112, s[68:69], v34, v34, 1.0
	v_rcp_f32_e32 v113, v112
	v_mov_b32_dpp v203, v202 row_mirror row_mask:0xf bank_mask:0xf bound_ctrl:1
	v_add_u32_e32 v204, s74, v146
	v_fma_f32 v114, -v112, v113, 1.0
	v_fmac_f32_e32 v113, v114, v113
	v_div_scale_f32 v114, vcc, 1.0, v34, 1.0
	v_mul_f32_e32 v115, v114, v113
	v_fma_f32 v118, -v112, v115, v114
	v_fmac_f32_e32 v115, v118, v113
	v_fma_f32 v112, -v112, v115, v114
	v_div_fmas_f32 v112, v112, v113, v115
	v_div_fixup_f32 v34, v112, v34, 1.0
	v_pk_mul_f32 v[114:115], v[104:105], v[34:35] op_sel_hi:[1,0]
	v_lshlrev_b32_e32 v118, 16, v84
	v_pk_mul_f32 v[104:105], v[114:115], v[116:117]
	v_pk_add_f32 v[116:117], v[116:117], -1.0 op_sel_hi:[1,0]
	v_pk_mul_f32 v[84:85], v[0:1], v[118:119]
	v_pk_fma_f32 v[116:117], v[4:5], v[116:117], 1.0 op_sel_hi:[1,1,0]
	v_pk_mul_f32 v[124:125], v[84:85], v[84:85]
	v_pk_mul_f32 v[108:109], v[116:117], v[108:109]
	v_pk_mul_f32 v[116:117], v[2:3], v[120:121]
	v_pk_mul_f32 v[112:113], v[106:107], v[34:35] op_sel_hi:[1,0]
	v_pk_mul_f32 v[122:123], v[116:117], v[116:117]
	v_lshlrev_b32_e32 v74, 16, v75
	v_pk_mov_b32 v[134:135], v[124:125], v[122:123] op_sel:[1,0]
	v_mov_b32_e32 v125, v123
	v_pk_add_f32 v[122:123], v[134:135], v[124:125]
	v_and_b32_e32 v75, 0xffff0000, v75
	v_add_f32_e32 v34, v122, v123
	v_pk_mul_f32 v[80:81], v[86:87], v[74:75]
	v_pk_add_f32 v[74:75], v[74:75], -1.0 op_sel_hi:[1,0]
	v_add_f32_dpp v34, v34, v34 quad_perm:[1,0,3,2] row_mask:0xf bank_mask:0xf bound_ctrl:1
	v_pk_fma_f32 v[74:75], v[6:7], v[74:75], 1.0 op_sel_hi:[1,1,0]
	v_lshlrev_b32_e32 v66, 16, v68
	v_add_f32_dpp v34, v34, v34 quad_perm:[2,3,0,1] row_mask:0xf bank_mask:0xf bound_ctrl:1
	v_pk_mul_f32 v[90:91], v[74:75], v[90:91]
	v_and_b32_e32 v67, 0xffff0000, v68
	v_add_f32_dpp v34, v34, v34 row_half_mirror row_mask:0xf bank_mask:0xf bound_ctrl:1
	v_lshlrev_b32_e32 v68, 16, v69
	v_and_b32_e32 v69, 0xffff0000, v69
	v_add_f32_dpp v34, v34, v34 row_mirror row_mask:0xf bank_mask:0xf bound_ctrl:1
	v_cmp_gt_f32_e32 vcc, s24, v34
	v_mul_f32_e32 v122, 0x4f800000, v34
	v_lshlrev_b32_e32 v98, 16, v99
	v_cndmask_b32_e32 v34, v34, v122, vcc
	v_sqrt_f32_e32 v122, v34
	v_and_b32_e32 v99, 0xffff0000, v99
	v_pk_mul_f32 v[106:107], v[112:113], v[98:99]
	v_pk_add_f32 v[98:99], v[98:99], -1.0 op_sel_hi:[1,0]
	v_add_u32_e32 v123, -1, v122
	v_fma_f32 v124, -v123, v122, v34
	v_cmp_ge_f32_e64 s[68:69], 0, v124
	v_add_u32_e32 v124, 1, v122
	v_pk_fma_f32 v[98:99], v[6:7], v[98:99], 1.0 op_sel_hi:[1,1,0]
	v_cndmask_b32_e64 v123, v122, v123, s[68:69]
	v_fma_f32 v122, -v124, v122, v34
	v_cmp_lt_f32_e64 s[68:69], 0, v122
	v_pk_mul_f32 v[110:111], v[98:99], v[110:111]
	v_lshlrev_b32_e32 v74, 16, v76
	v_cndmask_b32_e64 v122, v123, v124, s[68:69]
	v_mul_f32_e32 v123, 0x37800000, v122
	v_cndmask_b32_e32 v122, v122, v123, vcc
	v_cmp_class_f32_e32 vcc, v34, v229
	v_and_b32_e32 v75, 0xffff0000, v76
	v_lshlrev_b32_e32 v76, 16, v77
	v_cndmask_b32_e32 v34, v122, v34, vcc
	v_max_f32_e32 v34, 0x2b8cbccc, v34
	v_div_scale_f32 v122, s[68:69], v34, v34, 1.0
	v_rcp_f32_e32 v123, v122
	v_and_b32_e32 v77, 0xffff0000, v77
	v_lshlrev_b32_e32 v98, 16, v96
	v_and_b32_e32 v99, 0xffff0000, v96
	v_fma_f32 v124, -v122, v123, 1.0
	v_fmac_f32_e32 v123, v124, v123
	v_div_scale_f32 v124, vcc, 1.0, v34, 1.0
	v_mul_f32_e32 v125, v124, v123
	v_fma_f32 v134, -v122, v125, v124
	v_fmac_f32_e32 v125, v134, v123
	v_fma_f32 v122, -v122, v125, v124
	v_div_fmas_f32 v122, v122, v123, v125
	v_div_fixup_f32 v34, v122, v34, 1.0
	v_pk_mul_f32 v[122:123], v[116:117], v[34:35] op_sel_hi:[1,0]
	v_pk_mul_f32 v[124:125], v[84:85], v[34:35] op_sel_hi:[1,0]
	v_pk_mul_f32 v[116:117], v[122:123], v[8:9]
	v_pk_add_f32 v[8:9], v[8:9], -1.0 op_sel_hi:[1,0]
	v_pk_mul_f32 v[84:85], v[124:125], v[10:11]
	v_pk_add_f32 v[10:11], v[10:11], -1.0 op_sel_hi:[1,0]
	v_pk_fma_f32 v[8:9], v[6:7], v[8:9], 1.0 op_sel_hi:[1,1,0]
	v_pk_fma_f32 v[10:11], v[4:5], v[10:11], 1.0 op_sel_hi:[1,1,0]
	v_pk_mul_f32 v[120:121], v[8:9], v[120:121]
	v_sub_f32_e32 v9, 1.0, v137
	v_sub_f32_e32 v8, 1.0, v136
	v_pk_mul_f32 v[118:119], v[10:11], v[118:119]
	v_sub_f32_e32 v11, 1.0, v165
	v_sub_f32_e32 v10, 1.0, v164
	v_pk_mul_f32 v[164:165], v[102:103], v[128:129]
	v_pk_mul_f32 v[128:129], v[132:133], v[8:9]
	v_or_b32_e32 v8, v232, v24
	v_lshlrev_b32_e32 v34, 2, v8
	v_or_b32_e32 v8, v232, v143
	v_lshlrev_b32_e32 v171, 2, v8
	v_or_b32_e32 v8, v232, v144
	v_lshlrev_b32_e32 v173, 2, v8
	v_or_b32_e32 v8, v232, v145
	v_pk_mul_f32 v[134:135], v[164:165], v[130:131]
	v_lshlrev_b32_e32 v174, 2, v8
	ds_bpermute_b32 v8, v34, v128
	v_pk_mul_f32 v[126:127], v[134:135], v[10:11]
	ds_bpermute_b32 v10, v171, v128
	ds_bpermute_b32 v136, v173, v128
	ds_bpermute_b32 v9, v34, v129
	ds_bpermute_b32 v168, v174, v128
	ds_bpermute_b32 v11, v171, v129
	ds_bpermute_b32 v169, v173, v129
	ds_bpermute_b32 v137, v174, v129
	s_waitcnt lgkmcnt(7)
	v_cndmask_b32_e64 v130, v8, 1.0, s[42:43]
	s_waitcnt lgkmcnt(6)
	v_mul_f32_e32 v131, v130, v10
	v_cndmask_b32_e64 v130, v130, v131, s[44:45]
	s_waitcnt lgkmcnt(5)
	v_mul_f32_e32 v131, v130, v136
	v_cndmask_b32_e64 v130, v130, v131, s[46:47]
	s_waitcnt lgkmcnt(4)
	v_cndmask_b32_e64 v131, v9, 1.0, s[42:43]
	s_waitcnt lgkmcnt(2)
	v_mul_f32_e32 v170, v131, v11
	v_pk_mul_f32 v[8:9], v[8:9], v[10:11]
	s_waitcnt lgkmcnt(0)
; #define LAS __attribute__((address_space(3)))
; __device__ __forceinline__ void rw_scan(const bf16* R, const bf16* K, const bf16* V, const bf16* WM, const bf16* A, const float* k_k, const float* k_a, bf16* Y, LAS unsigned char* lds) {
;     ...
;                         const f32x4 r = bf4(cu.r[j]), k = bf4(cu.k[j]), wm = bf4(cu.wm[j]), a = bf4(cu.a[j]);
;                         const f32x4 kr = k * kkc;
;                         const float n2 = row16_sum((kr[0] * kr[0] + kr[1] * kr[1]) + (kr[2] * kr[2] + kr[3] * kr[3]));
;                         const float inv = 1.0f / fmaxf(sqrtf(n2), 1e-12f);
;                         kk[j] = kr * inv; be[j] = kk[j] * a; km[j] = k * (1.0f + (a - 1.0f) * kac); wv[j] = 1.0f - wm; rr[j] = r;
;                     }
;                     f32x4 g[4]; g[0] = wv[0]; g[1] = g[0] * wv[1]; g[2] = g[1] * wv[2]; g[3] = g[2] * wv[3];
;                     f32x4 pre = (f32x4){1.f, 1.f, 1.f, 1.f}, all = (f32x4){1.f, 1.f, 1.f, 1.f};
; #pragma unroll
;                     for (int x = 0; x < 4; ++x) {
;                         const float t0 = __shfl(g[3][x], fr), t1 = __shfl(g[3][x], 16 + fr), t2 = __shfl(g[3][x], 32 + fr), t3 = __shfl(g[3][x], 48 + fr);
;                         float p = 1.f; if (fq > 0) p *= t0; if (fq > 1) p *= t1; if (fq > 2) p *= t2;
;                         pre[x] = p; all[x] = (t0 * t1) * (t2 * t3);
;                     }
;                     unsigned kgp[4][2], bgp[4][2], abp[4][2];
;                     float kgt[4][4], bgt[4][4], abt[4][4];
; #pragma unroll
;                     for (int j = 0; j < 4; ++j) {
;                         const f32x4 Gs = pre * g[j], Gm = j ? pre * g[j - 1] : pre;
;                         f32x4 ginv; ginv[0] = __builtin_amdgcn_rcpf(Gs[0]); ginv[1] = __builtin_amdgcn_rcpf(Gs[1]); ginv[2] = __builtin_amdgcn_rcpf(Gs[2]); ginv[3] = __builtin_amdgcn_rcpf(Gs[3]);
;                         const f32x4 alb = kk[j] * Gm, rb = rr[j] * Gs, bet = be[j] * ginv, ktl = km[j] * ginv;
;                         const int s = 4 * fq + j;
;                         v2u o;
;                         o.x = pk2(alb[0], alb[1]); o.y = pk2(alb[2], alb[3]); *(LAS v2u*)(tmp + RWT_AB + s * 128 + 8 * fr) = o;
;                         o.x = pk2(bet[0], bet[1]); o.y = pk2(bet[2], bet[3]); *(LAS v2u*)(tmp + RWT_BT + s * 128 + 8 * fr) = o;
	v_pk_mul_f32 v[10:11], v[168:169], v[136:137]
	v_cndmask_b32_e64 v131, v131, v170, s[44:45]
	v_pk_mul_f32 v[8:9], v[8:9], v[10:11]
	ds_bpermute_b32 v10, v34, v126
	ds_bpermute_b32 v168, v171, v126
	v_mul_f32_e32 v170, v131, v169
	v_cndmask_b32_e64 v131, v131, v170, s[46:47]
	ds_bpermute_b32 v170, v173, v126
	ds_bpermute_b32 v11, v34, v127
	ds_bpermute_b32 v172, v174, v126
	ds_bpermute_b32 v169, v171, v127
	ds_bpermute_b32 v173, v173, v127
	ds_bpermute_b32 v171, v174, v127
	s_waitcnt lgkmcnt(7)
	v_cndmask_b32_e64 v34, v10, 1.0, s[42:43]
	s_waitcnt lgkmcnt(6)
	v_mul_f32_e32 v136, v34, v168
	v_cndmask_b32_e64 v34, v34, v136, s[44:45]
	s_waitcnt lgkmcnt(5)
	v_mul_f32_e32 v136, v34, v170
	v_cndmask_b32_e64 v136, v34, v136, s[46:47]
	s_waitcnt lgkmcnt(4)
	v_cndmask_b32_e64 v34, v11, 1.0, s[42:43]
	s_waitcnt lgkmcnt(2)
	v_mul_f32_e32 v137, v34, v169
	v_pk_mul_f32 v[10:11], v[10:11], v[168:169]
	s_waitcnt lgkmcnt(0)
	v_pk_mul_f32 v[168:169], v[172:173], v[170:171]
	v_cndmask_b32_e64 v34, v34, v137, s[44:45]
	v_pk_mul_f32 v[10:11], v[10:11], v[168:169]
	v_lshlrev_b32_e32 v168, 16, v64
	v_and_b32_e32 v169, 0xffff0000, v64
	v_mul_f32_e32 v137, v34, v173
	v_pk_add_f32 v[170:171], v[168:169], -1.0 op_sel_hi:[1,0]
	v_cndmask_b32_e64 v137, v34, v137, s[46:47]
	v_pk_fma_f32 v[170:171], v[4:5], v[170:171], 1.0 op_sel_hi:[1,1,0]
	v_add_f32_e32 v34, v202, v203
	v_pk_mul_f32 v[92:93], v[170:171], v[92:93]
	v_cmp_gt_f32_e32 vcc, s24, v34
	v_mul_f32_e32 v170, 0x4f800000, v34
	v_lshlrev_b32_e32 v64, 16, v65
	v_cndmask_b32_e32 v34, v34, v170, vcc
	v_sqrt_f32_e32 v170, v34
	v_and_b32_e32 v65, 0xffff0000, v65
	v_pk_add_f32 v[172:173], v[64:65], -1.0 op_sel_hi:[1,0]
	v_pk_mul_f32 v[102:103], v[102:103], v[136:137]
	v_pk_fma_f32 v[172:173], v[6:7], v[172:173], 1.0 op_sel_hi:[1,1,0]
	v_add_u32_e32 v171, -1, v170
	v_pk_mul_f32 v[94:95], v[172:173], v[94:95]
	v_fma_f32 v172, -v171, v170, v34
	v_cmp_ge_f32_e64 s[68:69], 0, v172
	v_add_u32_e32 v172, 1, v170
	v_pk_mul_f32 v[100:101], v[100:101], v[130:131]
	v_cndmask_b32_e64 v171, v170, v171, s[68:69]
	v_fma_f32 v170, -v172, v170, v34
	v_cmp_lt_f32_e64 s[68:69], 0, v170
	v_rcp_f32_e32 v176, v100
	v_rcp_f32_e32 v177, v101
	v_cndmask_b32_e64 v170, v171, v172, s[68:69]
	v_mul_f32_e32 v171, 0x37800000, v170
	v_cndmask_b32_e32 v170, v170, v171, vcc
	v_cmp_class_f32_e32 vcc, v34, v229
	v_rcp_f32_e32 v178, v102
	v_rcp_f32_e32 v179, v103
	v_cndmask_b32_e32 v34, v170, v34, vcc
	v_max_f32_e32 v34, 0x2b8cbccc, v34
	v_div_scale_f32 v170, s[68:69], v34, v34, 1.0
	v_rcp_f32_e32 v171, v170
	v_pk_mul_f32 v[94:95], v[94:95], v[178:179]
	v_pk_mul_f32 v[92:93], v[92:93], v[176:177]
	v_pk_mul_f32 v[86:87], v[86:87], v[102:103]
	v_fma_f32 v172, -v170, v171, 1.0
	v_fmac_f32_e32 v171, v172, v171
	v_div_scale_f32 v172, vcc, 1.0, v34, 1.0
	v_mul_f32_e32 v173, v172, v171
	v_fma_f32 v174, -v170, v173, v172
	v_fmac_f32_e32 v173, v174, v171
	v_fma_f32 v170, -v170, v173, v172
	v_div_fmas_f32 v170, v170, v171, v173
	v_div_fixup_f32 v34, v170, v34, 1.0
	v_pk_mul_f32 v[72:73], v[72:73], v[34:35] op_sel_hi:[1,0]
	v_pk_mul_f32 v[70:71], v[70:71], v[34:35] op_sel_hi:[1,0]
	v_pk_mul_f32 v[170:171], v[72:73], v[64:65]
	v_pk_mul_f32 v[168:169], v[70:71], v[168:169]
	v_lshlrev_b32_e32 v172, 16, v32
	v_and_b32_e32 v173, 0xffff0000, v32
	v_lshlrev_b32_e32 v174, 16, v33
	v_pk_mul_f32 v[32:33], v[72:73], v[136:137]
	v_pk_mul_f32 v[64:65], v[70:71], v[130:131]
	v_pk_mul_f32 v[170:171], v[170:171], v[178:179]
	v_pk_mul_f32 v[168:169], v[168:169], v[176:177]
	v_pk_mul_f32 v[70:71], v[102:103], v[174:175]
	v_pk_mul_f32 v[72:73], v[100:101], v[172:173]
	v_cvt_pk_bf16_f32 v172, v64, v65
	v_cvt_pk_bf16_f32 v173, v32, v33
	v_add_u32_e32 v34, v147, v154
	v_cvt_pk_bf16_f32 v174, v168, v169
	v_cvt_pk_bf16_f32 v175, v170, v171
	ds_write2st64_b64 v34, v[172:173], v[174:175] offset1:4
	v_cvt_pk_bf16_f32 v172, v92, v93
	v_cvt_pk_bf16_f32 v173, v94, v95
	ds_write_b64 v34, v[172:173] offset:4096
	v_cvt_pk_bf16_f32 v72, v72, v73
	v_cvt_pk_bf16_f32 v73, v70, v71
	v_add_u32_e32 v34, v204, v154
	ds_write_b64 v34, v[72:73] offset:2048
	v_pk_mul_f32 v[70:71], v[164:165], v[136:137]
	v_pk_mul_f32 v[72:73], v[166:167], v[130:131]
	v_rcp_f32_e32 v166, v70
	v_rcp_f32_e32 v164, v72
	v_rcp_f32_e32 v165, v73
	v_rcp_f32_e32 v167, v71
	v_pk_mul_f32 v[88:89], v[88:89], v[100:101]
	v_cvt_pk_bf16_f32 v101, v86, v87
	v_pk_mul_f32 v[78:79], v[78:79], v[164:165]
	v_pk_mul_f32 v[80:81], v[80:81], v[166:167]
	v_pk_mul_f32 v[90:91], v[90:91], v[166:167]
	v_pk_mul_f32 v[82:83], v[82:83], v[164:165]
	v_cvt_pk_bf16_f32 v100, v88, v89
	v_add_u32_e32 v34, v147, v155
	v_cvt_pk_bf16_f32 v102, v78, v79
	v_cvt_pk_bf16_f32 v103, v80, v81
	v_pk_mul_f32 v[68:69], v[70:71], v[68:69]
	v_pk_mul_f32 v[66:67], v[72:73], v[66:67]
	ds_write2st64_b64 v34, v[100:101], v[102:103] offset1:4
	v_cvt_pk_bf16_f32 v100, v82, v83
	v_cvt_pk_bf16_f32 v101, v90, v91
	ds_write_b64 v34, v[100:101] offset:4096
	v_cvt_pk_bf16_f32 v66, v66, v67
	v_cvt_pk_bf16_f32 v67, v68, v69
	v_add_u32_e32 v34, v204, v155
	ds_write_b64 v34, v[66:67] offset:2048
	v_mov_b32_e32 v66, v92
	v_mov_b32_e32 v67, v82
	v_mov_b32_e32 v82, v93
	v_mov_b32_e32 v92, v94
	v_mov_b32_e32 v93, v90
	v_mov_b32_e32 v90, v95
	v_pk_mul_f32 v[94:95], v[134:135], v[136:137]
	v_pk_mul_f32 v[102:103], v[132:133], v[130:131]
	v_rcp_f32_e32 v134, v94
	v_rcp_f32_e32 v132, v102
	v_rcp_f32_e32 v133, v103
	v_rcp_f32_e32 v135, v95
	v_pk_mul_f32 v[70:71], v[112:113], v[70:71]
	v_pk_mul_f32 v[72:73], v[114:115], v[72:73]
	v_pk_mul_f32 v[104:105], v[104:105], v[132:133]
	v_pk_mul_f32 v[106:107], v[106:107], v[134:135]
	v_pk_mul_f32 v[110:111], v[110:111], v[134:135]
; #define LAS __attribute__((address_space(3)))
; __device__ __forceinline__ void rw_scan(const bf16* R, const bf16* K, const bf16* V, const bf16* WM, const bf16* A, const float* k_k, const float* k_a, bf16* Y, LAS unsigned char* lds) {
;     ...
;                         o.x = pk2(alb[0], alb[1]); o.y = pk2(alb[2], alb[3]); *(LAS v2u*)(tmp + RWT_AB + s * 128 + 8 * fr) = o;
;                         o.x = pk2(bet[0], bet[1]); o.y = pk2(bet[2], bet[3]); *(LAS v2u*)(tmp + RWT_BT + s * 128 + 8 * fr) = o;
;                         o.x = pk2(ktl[0], ktl[1]); o.y = pk2(ktl[2], ktl[3]); *(LAS v2u*)(tmp + RWT_KT + s * 128 + 8 * fr) = o;
;                         o.x = pk2(rb[0], rb[1]); o.y = pk2(rb[2], rb[3]); *(LAS v2u*)(slot + RWS_RB + s * 128 + 8 * fr) = o;
; #pragma unroll
;                         for (int x = 0; x < 4; ++x) { kgt[x][j] = ktl[x] * all[x]; bgt[x][j] = -(bet[x] * all[x]); abt[x][j] = alb[x]; }
;                     }
; #pragma unroll
;                     for (int x = 0; x < 4; ++x) {
;                         const int kch = 4 * fr + x;
;                         v2u o;
;                         o.x = pk2(kgt[x][0], kgt[x][1]); o.y = pk2(kgt[x][2], kgt[x][3]); *(LAS v2u*)(slot + RWS_KGT + rwz(kch) * 32 + 8 * fq) = o;
;                         o.x = pk2(bgt[x][0], bgt[x][1]); o.y = pk2(bgt[x][2], bgt[x][3]); *(LAS v2u*)(slot + RWS_BGT + rwz(kch) * 32 + 8 * fq) = o;
;                         o.x = pk2(abt[x][0], abt[x][1]); o.y = pk2(abt[x][2], abt[x][3]); *(LAS v2u*)(tmp + RWT_ABT + rwz(kch) * 32 + 8 * fq) = o;
;                     }
;                     if (fq == 0) *(LAS f32x4*)(slot + RWS_G15 + 16 * fr) = all;
;                     const unsigned vlo = (unsigned)cu.v[0] | ((unsigned)cu.v[1] << 16), vhi = (unsigned)cu.v[2] | ((unsigned)cu.v[3] << 16);
;                     { v2u o; o.x = vlo; o.y = vhi; *(LAS v2u*)(slot + RWS_VCI + 8 * lane) = o; }
;                     LDS_WAIT(); asm volatile("" ::: "memory");
;                     f32x4 nac = (f32x4){0.f, 0.f, 0.f, 0.f}, kat = nac, krt = nac, nrt = nac;
; #pragma unroll
;                     for (int p = 0; p < 2; ++p) {
;                         const int kb = (32 * p + 8 * fq) * 2;
;                         const bf16x8 oAB = lds_op16(tmp + RWT_AB, fr, kb), oBT = lds_op16(tmp + RWT_BT, fr, kb), oKT = lds_op16(tmp + RWT_KT, fr, kb), oRB = lds_op16(slot + RWS_RB, fr, kb);
	v_pk_mul_f32 v[108:109], v[108:109], v[132:133]
	v_cvt_pk_bf16_f32 v112, v72, v73
	v_cvt_pk_bf16_f32 v113, v70, v71
	v_add_u32_e32 v34, v147, v156
	v_cvt_pk_bf16_f32 v114, v104, v105
	v_cvt_pk_bf16_f32 v115, v106, v107
	v_pk_mul_f32 v[76:77], v[94:95], v[76:77]
	v_pk_mul_f32 v[74:75], v[102:103], v[74:75]
	ds_write2st64_b64 v34, v[112:113], v[114:115] offset1:4
	v_cvt_pk_bf16_f32 v112, v108, v109
	v_cvt_pk_bf16_f32 v113, v110, v111
	ds_write_b64 v34, v[112:113] offset:4096
	v_cvt_pk_bf16_f32 v74, v74, v75
	v_cvt_pk_bf16_f32 v75, v76, v77
	v_add_u32_e32 v34, v204, v156
	ds_write_b64 v34, v[74:75] offset:2048
	v_pk_mul_f32 v[74:75], v[126:127], v[136:137]
	v_pk_mul_f32 v[76:77], v[128:129], v[130:131]
	v_rcp_f32_e32 v114, v74
	v_rcp_f32_e32 v112, v76
	v_rcp_f32_e32 v113, v77
	v_rcp_f32_e32 v115, v75
	v_lshlrev_b32_e32 v96, 16, v97
	v_and_b32_e32 v97, 0xffff0000, v97
	v_pk_mul_f32 v[94:95], v[122:123], v[94:95]
	v_pk_mul_f32 v[102:103], v[124:125], v[102:103]
	v_pk_mul_f32 v[74:75], v[74:75], v[96:97]
	v_pk_mul_f32 v[96:97], v[116:117], v[114:115]
	v_pk_mul_f32 v[84:85], v[84:85], v[112:113]
	v_pk_mul_f32 v[76:77], v[76:77], v[98:99]
	v_pk_mul_f32 v[98:99], v[120:121], v[114:115]
	v_pk_mul_f32 v[112:113], v[118:119], v[112:113]
	v_cvt_pk_bf16_f32 v114, v102, v103
	v_cvt_pk_bf16_f32 v115, v94, v95
	v_add_u32_e32 v34, v147, v157
	v_cvt_pk_bf16_f32 v116, v84, v85
	v_cvt_pk_bf16_f32 v117, v96, v97
	ds_write2st64_b64 v34, v[114:115], v[116:117] offset1:4
	v_cvt_pk_bf16_f32 v114, v112, v113
	v_cvt_pk_bf16_f32 v115, v98, v99
	ds_write_b64 v34, v[114:115] offset:4096
	v_cvt_pk_bf16_f32 v76, v76, v77
	v_cvt_pk_bf16_f32 v77, v74, v75
	v_add_u32_e32 v34, v204, v157
	v_mov_b32_e32 v68, v168
	v_mov_b32_e32 v69, v78
	ds_write_b64 v34, v[76:77] offset:2048
	v_mov_b32_e32 v74, v108
	v_mov_b32_e32 v75, v112
	v_mov_b32_e32 v76, v104
	v_mov_b32_e32 v77, v84
	v_pk_mul_f32 v[66:67], v[8:9], v[66:67] op_sel_hi:[0,1]
	v_pk_mul_f32 v[68:69], v[68:69], v[8:9] op_sel_hi:[1,0] neg_lo:[0,1] neg_hi:[0,1]
	v_pk_mul_f32 v[74:75], v[8:9], v[74:75] op_sel_hi:[0,1]
	v_pk_mul_f32 v[76:77], v[76:77], v[8:9] op_sel_hi:[1,0] neg_lo:[0,1] neg_hi:[0,1]
	v_add_u32_e32 v34, s74, v139
	v_mov_b32_e32 v78, v169
	v_mov_b32_e32 v112, v109
	v_mov_b32_e32 v84, v105
	v_cvt_pk_bf16_f32 v66, v66, v67
	v_cvt_pk_bf16_f32 v67, v74, v75
	v_add_u32_e32 v74, v34, v158
	v_cvt_pk_bf16_f32 v68, v68, v69
	v_cvt_pk_bf16_f32 v69, v76, v77
	v_pk_mul_f32 v[82:83], v[8:9], v[82:83] op_sel:[1,0]
	v_pk_mul_f32 v[78:79], v[78:79], v[8:9] op_sel:[0,1] neg_lo:[0,1] neg_hi:[0,1]
	v_pk_mul_f32 v[108:109], v[8:9], v[112:113] op_sel:[1,0]
	v_pk_mul_f32 v[84:85], v[84:85], v[8:9] op_sel:[0,1] neg_lo:[0,1] neg_hi:[0,1]
	ds_write2st64_b64 v74, v[66:67], v[68:69] offset0:8 offset1:12
	v_cvt_pk_bf16_f32 v66, v64, v88
	v_cvt_pk_bf16_f32 v67, v72, v102
	v_add_u32_e32 v64, v148, v158
	v_mov_b32_e32 v100, v170
	v_mov_b32_e32 v101, v80
	v_mov_b32_e32 v104, v110
	v_mov_b32_e32 v105, v98
	v_mov_b32_e32 v112, v106
	v_mov_b32_e32 v113, v96
	ds_write_b64 v64, v[66:67] offset:6144
	v_cvt_pk_bf16_f32 v66, v82, v83
	v_cvt_pk_bf16_f32 v67, v108, v109
	v_add_u32_e32 v64, v34, v159
	v_cvt_pk_bf16_f32 v68, v78, v79
	v_cvt_pk_bf16_f32 v69, v84, v85
	v_pk_mul_f32 v[92:93], v[10:11], v[92:93] op_sel_hi:[0,1]
	v_pk_mul_f32 v[100:101], v[100:101], v[10:11] op_sel_hi:[1,0] neg_lo:[0,1] neg_hi:[0,1]
	v_pk_mul_f32 v[104:105], v[10:11], v[104:105] op_sel_hi:[0,1]
	v_pk_mul_f32 v[112:113], v[112:113], v[10:11] op_sel_hi:[1,0] neg_lo:[0,1] neg_hi:[0,1]
	ds_write2st64_b64 v64, v[66:67], v[68:69] offset0:8 offset1:12
	v_cvt_pk_bf16_f32 v64, v65, v89
	v_cvt_pk_bf16_f32 v65, v73, v103
	v_add_u32_e32 v66, v148, v159
	v_mov_b32_e32 v80, v171
	v_mov_b32_e32 v98, v111
	v_mov_b32_e32 v96, v107
	ds_write_b64 v66, v[64:65] offset:6144
	v_cvt_pk_bf16_f32 v64, v92, v93
	v_cvt_pk_bf16_f32 v65, v104, v105
	v_add_u32_e32 v68, v34, v160
	v_cvt_pk_bf16_f32 v66, v100, v101
	v_cvt_pk_bf16_f32 v67, v112, v113
	v_pk_mul_f32 v[90:91], v[10:11], v[90:91] op_sel:[1,0]
	v_pk_mul_f32 v[80:81], v[80:81], v[10:11] op_sel:[0,1] neg_lo:[0,1] neg_hi:[0,1]
	v_pk_mul_f32 v[98:99], v[10:11], v[98:99] op_sel:[1,0]
	v_pk_mul_f32 v[96:97], v[96:97], v[10:11] op_sel:[0,1] neg_lo:[0,1] neg_hi:[0,1]
	ds_write2st64_b64 v68, v[64:65], v[66:67] offset0:8 offset1:12
	v_cvt_pk_bf16_f32 v64, v32, v86
	v_cvt_pk_bf16_f32 v65, v70, v94
	v_add_u32_e32 v32, v148, v160
	ds_write_b64 v32, v[64:65] offset:6144
	v_cvt_pk_bf16_f32 v64, v90, v91
	v_cvt_pk_bf16_f32 v65, v98, v99
	v_add_u32_e32 v32, v34, v161
	v_cvt_pk_bf16_f32 v66, v80, v81
	v_cvt_pk_bf16_f32 v67, v96, v97
	ds_write2st64_b64 v32, v[64:65], v[66:67] offset0:8 offset1:12
	v_cvt_pk_bf16_f32 v32, v33, v87
	v_cvt_pk_bf16_f32 v33, v71, v95
	v_add_u32_e32 v34, v148, v161
	ds_write_b64 v34, v[32:33] offset:6144
	s_and_saveexec_b64 s[68:69], s[42:43]
	v_add_u32_e32 v32, s74, v149
	ds_write_b128 v32, v[8:11] offset:8192
	s_or_b64 exec, exec, s[68:69]
	v_lshlrev_b32_e32 v8, 16, v201
	v_lshlrev_b32_e32 v9, 16, v35
	v_or_b32_sdwa v8, v8, v200 dst_sel:DWORD dst_unused:UNUSED_PAD src0_sel:DWORD src1_sel:WORD_0
	v_or_b32_sdwa v9, v9, v199 dst_sel:DWORD dst_unused:UNUSED_PAD src0_sel:DWORD src1_sel:WORD_0
	v_add_u32_e32 v10, s74, v140
	ds_write_b64 v10, v[8:9] offset:10496
	ds_read_b128 v[32:35], v194 offset:2048
	ds_read_b128 v[64:67], v194
	ds_read_b128 v[68:71], v194 offset:64
	ds_read_b128 v[72:75], v194 offset:2112
	ds_read_b128 v[80:83], v194 offset:4096
	ds_read_b128 v[84:87], v194 offset:4160
	v_add3_u32 v10, s74, v138, v141
	ds_read_b128 v[88:91], v10 offset:2048
	ds_read_b128 v[92:95], v10 offset:2112
	s_waitcnt lgkmcnt(6)
; #define LAS __attribute__((address_space(3)))
; #define LDS_WAIT() asm volatile("s_waitcnt lgkmcnt(0)" ::: "memory")
; __device__ __forceinline__ unsigned pk2(float lo, float hi) { const f32x2_t v = {lo, hi}; const bf16x2_t b = __builtin_convertvector(v, bf16x2_t); return __builtin_bit_cast(unsigned, b); }
; __device__ __forceinline__ void rw_scan(const bf16* R, const bf16* K, const bf16* V, const bf16* WM, const bf16* A, const float* k_k, const float* k_a, bf16* Y, LAS unsigned char* lds) {
;     ...
;                     for (int p = 0; p < 2; ++p) {
;                         const int kb = (32 * p + 8 * fq) * 2;
;                         const bf16x8 oAB = lds_op16(tmp + RWT_AB, fr, kb), oBT = lds_op16(tmp + RWT_BT, fr, kb), oKT = lds_op16(tmp + RWT_KT, fr, kb), oRB = lds_op16(slot + RWS_RB, fr, kb);
;                         nac = __builtin_amdgcn_mfma_f32_16x16x32_bf16(oBT, oAB, nac, 0, 0, 0);
;                         kat = __builtin_amdgcn_mfma_f32_16x16x32_bf16(oKT, oAB, kat, 0, 0, 0);
;                         krt = __builtin_amdgcn_mfma_f32_16x16x32_bf16(oKT, oRB, krt, 0, 0, 0);
;                         nrt = __builtin_amdgcn_mfma_f32_16x16x32_bf16(oBT, oRB, nrt, 0, 0, 0);
;                     }
; #pragma unroll
;                     for (int i = 0; i < 4; ++i) { const int rr_ = 4 * fq + i;
;                         if (rr_ >= fr) { nac[i] = 0.f; kat[i] = 0.f; }
;                         if (rr_ > fr) { krt[i] = 0.f; nrt[i] = 0.f; } }
;                     { u32x4_t o; o.x = pk2(krt[0], krt[1]); o.y = pk2(krt[2], krt[3]); o.z = pk2(-nrt[0], -nrt[1]); o.w = pk2(-nrt[2], -nrt[3]); *(LAS u32x4_t*)(slot + RWS_KNI + 16 * lane) = o; }
;                     LDS_WAIT(); asm volatile("" ::: "memory");
;                     *(LAS f32x4*)(tmp + RWT_NM + (fr * 16 + 4 * fq) * 4) = nac;
;                     LDS_WAIT(); asm volatile("" ::: "memory");
;                     float Tc[16];
;                     f32x4 nvv[16][4];
;     ...
;                     RW_LD_ROWS(1, 8) RW_LD_ROWS(9, 12)
;                     asm volatile("" ::: "memory");
;                     RW_DO_ROWS(0, 8)
;                     RW_LD_ROWS(13, 15)
;                     asm volatile("" ::: "memory");
;                     RW_DO_ROWS(9, 12)
;                     RW_DO_ROWS(13, 15)
	v_mfma_f32_16x16x32_bf16 v[76:79], v[32:35], v[64:67], 0
	v_mov_b32_e32 v10, s93
	v_add_u32_e32 v199, s74, v27
	s_or_b64 vcc, s[64:65], s[48:49]
	s_waitcnt lgkmcnt(1)
	v_mfma_f32_16x16x32_bf16 v[32:35], v[32:35], v[88:91], 0
	v_mov_b32_e32 v237, v236
	v_mfma_f32_16x16x32_bf16 v[64:67], v[80:83], v[64:67], 0
	v_mfma_f32_16x16x32_bf16 v[80:83], v[80:83], v[88:91], 0
	s_waitcnt lgkmcnt(0)
	v_mfma_f32_16x16x32_bf16 v[32:35], v[72:75], v[92:95], v[32:35]
	v_mfma_f32_16x16x32_bf16 v[76:79], v[72:75], v[68:71], v[76:79]
	v_mov_b32_e32 v72, s93
	s_nop 5
	v_cndmask_b32_e64 v11, v32, v72, s[50:51]
	v_mfma_f32_16x16x32_bf16 v[72:75], v[84:87], v[92:95], v[80:83]
	v_mfma_f32_16x16x32_bf16 v[64:67], v[84:87], v[68:71], v[64:67]
	v_cndmask_b32_e64 v71, 0, v79, s[54:55]
	s_nop 5
	v_cndmask_b32_e64 v10, v72, v10, s[50:51]
	v_cndmask_b32_e64 v10, v10, v72, s[48:49]
	v_cndmask_b32_e64 v72, 0, v73, s[48:49]
	v_cvt_pk_bf16_f32 v72, v10, v72
	v_cndmask_b32_e64 v10, v11, v32, s[48:49]
	v_cndmask_b32_e64 v11, 0, v33, s[48:49]
	v_cndmask_b32_e64 v73, v74, 0, s[52:53]
	v_cndmask_b32_e64 v74, v75, 0, s[56:57]
	v_xor_b32_e32 v10, 0x80000000, v10
	v_xor_b32_e32 v11, 0x80000000, v11
	v_cvt_pk_bf16_f32 v73, v73, v74
	v_cvt_pk_bf16_f32 v74, v10, v11
	v_cndmask_b32_e64 v10, v34, 0, s[52:53]
	v_xor_b32_e32 v10, 0x80000000, v10
	v_cndmask_b32_e64 v11, -v35, v251, s[56:57]
	v_cvt_pk_bf16_f32 v75, v10, v11
	ds_write_b128 v199, v[72:75] offset:8448
	v_cndmask_b32_e64 v70, 0, v78, s[62:63]
	v_cndmask_b32_e64 v69, 0, v77, s[64:65]
	v_cndmask_b32_e32 v68, 0, v76, vcc
	ds_write_b128 v195, v[68:71]
	v_mov_b32_e32 v10, s90
	ds_read_b128 v[32:35], v10 offset:64
	ds_read_b128 v[68:71], v10 offset:128
	ds_read_b128 v[70:73], v10 offset:192
	ds_read_b128 v[74:77], v10 offset:256
	ds_read_b128 v[78:81], v10 offset:320
	ds_read_b128 v[82:85], v10 offset:336
	ds_read_b128 v[84:87], v10 offset:384
	ds_read_b128 v[88:91], v10 offset:400
	ds_read_b128 v[90:93], v10 offset:448
	ds_read_b128 v[94:97], v10 offset:464
	ds_read_b128 v[98:101], v10 offset:512
	ds_read_b128 v[102:105], v10 offset:528
	ds_read_b128 v[106:109], v10 offset:576
	s_waitcnt lgkmcnt(12)
	ds_read_b128 v[110:113], v10 offset:592
	ds_read_b128 v[114:117], v10 offset:608
	s_waitcnt lgkmcnt(12)
	v_fma_f32 v11, -v162, v32, v163
	v_fma_f32 v32, -v162, v68, v180
	ds_read_b128 v[116:119], v10 offset:640
	ds_read_b128 v[120:123], v10 offset:656
	ds_read_b128 v[124:127], v10 offset:672
	s_waitcnt lgkmcnt(3)
	v_fma_f32 v115, -v69, v11, v32
	v_fma_f32 v32, -v162, v70, v181
	ds_read_b128 v[126:129], v10 offset:704
	ds_read_b128 v[130:133], v10 offset:720
	ds_read_b128 v[134:137], v10 offset:736
	ds_read_b128 v[164:167], v10 offset:768
	ds_read_b128 v[168:171], v10 offset:784
	ds_read_b128 v[172:175], v10 offset:800
	v_fma_f32 v32, -v71, v11, v32
	s_waitcnt lgkmcnt(3)
	v_fma_f32 v137, -v72, v115, v32
	v_fma_f32 v32, -v162, v74, v182
	v_fma_f32 v32, -v11, v75, v32
	v_fma_f32 v32, -v76, v115, v32
	v_fma_f32 v200, -v77, v137, v32
	v_fma_f32 v32, -v162, v78, v183
	v_fma_f32 v32, -v11, v79, v32
	v_fma_f32 v32, -v80, v115, v32
	v_fma_f32 v32, -v81, v137, v32
	v_fma_f32 v201, -v82, v200, v32
	v_fma_f32 v32, -v162, v84, v184
	v_fma_f32 v32, -v11, v85, v32
	v_fma_f32 v32, -v115, v86, v32
	v_fma_f32 v32, -v87, v137, v32
	v_fma_f32 v32, -v88, v200, v32
	v_fma_f32 v202, -v89, v201, v32
	v_fma_f32 v32, -v162, v90, v185
	v_fma_f32 v32, -v11, v91, v32
	v_fma_f32 v32, -v115, v92, v32
	v_fma_f32 v32, -v137, v93, v32
	v_fma_f32 v32, -v200, v94, v32
	v_fma_f32 v32, -v95, v201, v32
	v_fma_f32 v203, -v96, v202, v32
	v_fma_f32 v32, -v162, v98, v186
	v_fma_f32 v32, -v11, v99, v32
	v_fma_f32 v32, -v115, v100, v32
	v_fma_f32 v32, -v137, v101, v32
	v_fma_f32 v32, -v200, v102, v32
	v_fma_f32 v32, -v201, v103, v32
	v_fma_f32 v32, -v104, v202, v32
	v_fma_f32 v104, -v105, v203, v32
	ds_read_b128 v[32:35], v10 offset:832
	ds_read_b128 v[68:71], v10 offset:848
	ds_read_b128 v[72:75], v10 offset:864
	ds_read_b128 v[76:79], v10 offset:880
	ds_read_b128 v[78:81], v10 offset:896
	ds_read_b128 v[82:85], v10 offset:912
	ds_read_b128 v[86:89], v10 offset:928
	ds_read_b128 v[90:93], v10 offset:944
	ds_read_b128 v[92:95], v10 offset:960
	ds_read_b128 v[96:99], v10 offset:976
	ds_read_b128 v[100:103], v10 offset:992
	ds_read_b128 v[176:179], v10 offset:1008
	s_waitcnt lgkmcnt(7)
	v_fma_f32 v10, -v162, v106, v187
	v_fma_f32 v77, -v162, v116, v188
	v_fma_f32 v105, -v162, v126, v189
	v_fma_f32 v106, -v162, v164, v190
	v_fma_f32 v32, -v162, v32, v191
	v_fma_f32 v10, -v11, v107, v10
	v_fma_f32 v77, -v11, v117, v77
	v_fma_f32 v105, -v11, v127, v105
	v_fma_f32 v106, -v11, v165, v106
	v_fma_f32 v32, -v11, v33, v32
	v_fma_f32 v10, -v115, v108, v10
	v_fma_f32 v77, -v115, v118, v77
	v_fma_f32 v105, -v115, v128, v105
	v_fma_f32 v106, -v115, v166, v106
	v_fma_f32 v32, -v115, v34, v32
	v_fma_f32 v10, -v137, v109, v10
	v_fma_f32 v77, -v137, v119, v77
	v_fma_f32 v105, -v137, v129, v105
	v_fma_f32 v106, -v137, v167, v106
	v_fma_f32 v32, -v137, v35, v32
	v_fma_f32 v33, -v162, v78, v192
	s_waitcnt lgkmcnt(3)
; #define LAS __attribute__((address_space(3)))
; __device__ __forceinline__ void rw_scan(const bf16* R, const bf16* K, const bf16* V, const bf16* WM, const bf16* A, const float* k_k, const float* k_a, bf16* Y, LAS unsigned char* lds) {
;     ...
;                     RW_DO_ROWS(0, 8)
;                     RW_LD_ROWS(13, 15)
;                     asm volatile("" ::: "memory");
;                     RW_DO_ROWS(9, 12)
;                     RW_DO_ROWS(13, 15)
;     ...
; #pragma unroll
;                     for (int e = 0; e < 4; ++e) {
;                         float tv = Tc[0];
; #pragma unroll
;                         for (int s = 0; s < 16; ++s) if (s == 4 * fq + e) tv = Tc[s];
;                         *(LAS unsigned short*)(tmp + RWT_TM + ((4 * fq + e) * 16 + fr) * 2) = (unsigned short)f2bf(tv);
;                     }
;                     LDS_WAIT(); asm volatile("" ::: "memory");
;                     const v2u tq = lds_8(tmp + RWT_TM + (fr * 16 + 4 * fq) * 2);
;                     const bf16x8 opT = mk8(tq.x, tq.y, 0u, 0u);
;                     f32x4 xac = __builtin_amdgcn_mfma_f32_16x16x32_bf16(mk8(pk2(kat[0], kat[1]), pk2(kat[2], kat[3]), 0u, 0u), mk8(vlo, vhi, 0u, 0u), (f32x4){0.f, 0.f, 0.f, 0.f}, 0, 0, 0);
;                     const f32x4 wvv = __builtin_amdgcn_mfma_f32_16x16x32_bf16(opT, mk8(pk2(xac[0], xac[1]), pk2(xac[2], xac[3]), 0u, 0u), (f32x4){0.f, 0.f, 0.f, 0.f}, 0, 0, 0);
;                     *(LAS f32x4*)(slot + RWS_WVI + 16 * lane) = wvv;
;                     f32x4 aht[4];
; #pragma unroll
;                     for (int nt = 0; nt < 4; ++nt) {
;                         const v2u ab = lds_8(tmp + RWT_ABT + rwz(16 * nt + fr) * 32 + 8 * fq);
;                         aht[nt] = __builtin_amdgcn_mfma_f32_16x16x32_bf16(mk8(ab.x, ab.y, 0u, 0u), opT, (f32x4){0.f, 0.f, 0.f, 0.f}, 0, 0, 0);
;                     }
; #pragma unroll
;                     for (int p = 0; p < 2; ++p) { u32x4_t o; o.x = pk2(aht[2 * p][0], aht[2 * p][1]); o.y = pk2(aht[2 * p][2], aht[2 * p][3]); o.z = pk2(aht[2 * p + 1][0], aht[2 * p + 1][1]); o.w = pk2(aht[2 * p + 1][2], aht[2 * p + 1][3]);
;                         *(LAS u32x4_t*)(slot + RWS_AH + (p * 64 + lane) * 16) = o; }
;                     LDS_WAIT(); asm volatile("" ::: "memory");
;                     if (lane == 0) flg[cj % RW_NSLOT] = (unsigned)(cj + 1);
	v_fma_f32 v34, -v162, v92, v193
	v_fma_f32 v10, -v200, v110, v10
	v_fma_f32 v77, -v200, v120, v77
	v_fma_f32 v105, -v200, v130, v105
	v_fma_f32 v106, -v200, v168, v106
	v_fma_f32 v32, -v200, v68, v32
	v_fma_f32 v33, -v11, v79, v33
	v_fma_f32 v34, -v11, v93, v34
	v_fma_f32 v10, -v201, v111, v10
	v_fma_f32 v77, -v201, v121, v77
	v_fma_f32 v105, -v201, v131, v105
	v_fma_f32 v106, -v201, v169, v106
	v_fma_f32 v32, -v201, v69, v32
	v_fma_f32 v33, -v115, v80, v33
	v_fma_f32 v34, -v115, v94, v34
	v_fma_f32 v10, -v112, v202, v10
	v_fma_f32 v77, -v202, v122, v77
	v_fma_f32 v105, -v202, v132, v105
	v_fma_f32 v106, -v202, v170, v106
	v_fma_f32 v32, -v202, v70, v32
	v_fma_f32 v33, -v137, v81, v33
	v_fma_f32 v34, -v137, v95, v34
	v_fma_f32 v10, -v113, v203, v10
	v_fma_f32 v77, -v123, v203, v77
	v_fma_f32 v105, -v203, v133, v105
	v_fma_f32 v106, -v203, v171, v106
	v_fma_f32 v32, -v203, v71, v32
	v_fma_f32 v33, -v200, v82, v33
	s_waitcnt lgkmcnt(2)
	v_fma_f32 v34, -v200, v96, v34
	v_fma_f32 v10, -v114, v104, v10
	v_fma_f32 v77, -v124, v104, v77
	v_fma_f32 v105, -v104, v134, v105
	v_fma_f32 v106, -v104, v172, v106
	v_fma_f32 v32, -v104, v72, v32
	v_fma_f32 v33, -v201, v83, v33
	v_fma_f32 v34, -v201, v97, v34
	v_fma_f32 v77, -v125, v10, v77
	v_fma_f32 v105, -v135, v10, v105
	v_fma_f32 v106, -v10, v173, v106
	v_fma_f32 v32, -v10, v73, v32
	v_fma_f32 v33, -v202, v84, v33
	v_fma_f32 v34, -v202, v98, v34
	v_fma_f32 v105, -v136, v77, v105
	v_fma_f32 v106, -v174, v77, v106
	v_fma_f32 v32, -v77, v74, v32
	v_fma_f32 v33, -v203, v85, v33
	v_fma_f32 v34, -v203, v99, v34
	v_cndmask_b32_e64 v11, v162, v11, s[42:43]
	v_fma_f32 v106, -v175, v105, v106
	v_fma_f32 v32, -v75, v105, v32
	v_fma_f32 v33, -v104, v86, v33
	s_waitcnt lgkmcnt(1)
	v_fma_f32 v34, -v104, v100, v34
	v_cndmask_b32_e64 v11, v11, v201, s[58:59]
	v_fma_f32 v32, -v76, v106, v32
	v_fma_f32 v33, -v10, v87, v33
	v_fma_f32 v34, -v10, v101, v34
	v_cndmask_b32_e64 v10, v11, v10, s[60:61]
	v_cndmask_b32_e64 v10, v10, v32, s[46:47]
	v_fma_f32 v33, -v77, v88, v33
	v_cvt_pk_bf16_f32 v10, v10, s0
	v_fma_f32 v33, -v105, v89, v33
	ds_write_b16 v196, v10 offset:2080
	v_cndmask_b32_e64 v10, v162, v115, s[42:43]
	v_fma_f32 v33, -v90, v106, v33
	v_cndmask_b32_e64 v10, v10, v202, s[58:59]
	v_fma_f32 v33, -v91, v32, v33
	v_cndmask_b32_e64 v10, v10, v77, s[60:61]
	v_fma_f32 v34, -v77, v102, v34
	v_cndmask_b32_e64 v10, v10, v33, s[46:47]
	v_fma_f32 v34, -v105, v103, v34
	v_cvt_pk_bf16_f32 v10, v10, s0
	s_waitcnt lgkmcnt(1)
	v_fma_f32 v34, -v106, v176, v34
	ds_write_b16 v196, v10 offset:2112
	v_cndmask_b32_e64 v10, v162, v137, s[42:43]
	v_fma_f32 v34, -v177, v32, v34
	v_cndmask_b32_e64 v35, v162, v200, s[58:59]
	v_cndmask_b32_e64 v10, v10, v203, s[58:59]
	v_fma_f32 v34, -v178, v33, v34
	v_cndmask_b32_e64 v35, v35, v104, s[60:61]
	v_cndmask_b32_e64 v10, v10, v105, s[60:61]
	v_cndmask_b32_e64 v35, v35, v106, s[46:47]
	v_cndmask_b32_e64 v10, v10, v34, s[46:47]
	v_cvt_pk_bf16_f32 v35, v35, s0
	v_cvt_pk_bf16_f32 v10, v10, s0
	ds_write_b16 v196, v35 offset:2048
	ds_write_b16 v196, v10 offset:2144
	v_cndmask_b32_e64 v10, 0, v67, s[54:55]
	v_cndmask_b32_e64 v11, 0, v66, s[62:63]
	v_cndmask_b32_e64 v32, 0, v65, s[64:65]
	v_cndmask_b32_e32 v33, 0, v64, vcc
	v_cvt_pk_bf16_f32 v32, v33, v32
	v_cvt_pk_bf16_f32 v33, v11, v10
	v_mov_b32_e32 v34, v236
	v_mov_b32_e32 v35, v236
	ds_read_b64 v[234:235], v197 offset:2048
	v_add_u32_e32 v80, v148, v150
	v_add_u32_e32 v81, v148, v151
	v_add_u32_e32 v82, v148, v152
	v_add_u32_e32 v83, v148, v153
	ds_read_b64 v[72:73], v80 offset:6144
	ds_read_b64 v[76:77], v81 offset:6144
	ds_read_b64 v[64:65], v82 offset:6144
	ds_read_b64 v[68:69], v83 offset:6144
	v_mov_b32_e32 v10, v236
	v_mov_b32_e32 v11, v236
	v_mov_b32_e32 v66, v236
	v_mov_b32_e32 v67, v236
	v_mov_b32_e32 v70, v236
	v_mov_b32_e32 v71, v236
	v_mov_b32_e32 v74, v236
	v_mov_b32_e32 v75, v236
	v_mov_b32_e32 v78, v236
	v_mov_b32_e32 v79, v236
	v_mfma_f32_16x16x32_bf16 v[8:11], v[32:35], v[8:11], 0
	s_waitcnt lgkmcnt(0)
	v_mfma_f32_16x16x32_bf16 v[84:87], v[72:75], v[234:237], 0
	v_mfma_f32_16x16x32_bf16 v[32:35], v[76:79], v[234:237], 0
	v_mfma_f32_16x16x32_bf16 v[64:67], v[64:67], v[234:237], 0
	v_mfma_f32_16x16x32_bf16 v[68:71], v[68:71], v[234:237], 0
	s_nop 3
	v_cvt_pk_bf16_f32 v8, v8, v9
	v_cvt_pk_bf16_f32 v9, v10, v11
	v_mov_b32_e32 v10, v236
	v_mov_b32_e32 v11, v236
	s_nop 1
	v_mfma_f32_16x16x32_bf16 v[8:11], v[234:237], v[8:11], 0
	v_cvt_pk_bf16_f32 v72, v84, v85
	v_cvt_pk_bf16_f32 v73, v86, v87
	v_cvt_pk_bf16_f32 v74, v32, v33
	v_cvt_pk_bf16_f32 v75, v34, v35
	ds_write_b128 v199, v[72:75]
	v_cvt_pk_bf16_f32 v76, v64, v65
	v_cvt_pk_bf16_f32 v77, v66, v67
	v_cvt_pk_bf16_f32 v78, v68, v69
	v_cvt_pk_bf16_f32 v79, v70, v71
	ds_write_b128 v199, v[76:79] offset:1024
	s_nop 1
	ds_write_b128 v199, v[8:11] offset:9472
	s_waitcnt lgkmcnt(0)
	s_and_saveexec_b64 s[68:69], s[40:41]
	s_cbranch_execz .LBB0_495
	s_lshl_b32 s75, s92, 2
	s_add_i32 s75, s75, 0
	s_add_i32 s74, s89, 1
	s_add_i32 s75, s75, 0x26c00
	v_mov_b32_e32 v8, s75
	v_mov_b32_e32 v9, s74
	ds_write_b32 v8, v9
	s_branch .LBB0_495
